# v69 + retention backward pass: OF rows 0-2 requested at the start of the causal-mask stage (register reassignment), row 3 at its end, per-row counted waits
# baseline (speedup 1.0000x reference)
.Lre_nov:
	s_and_b64 vcc, exec, s[46:47]
	s_cbranch_vccz .Lre_noof0
	s_add_u32 s16, s40, s28
	s_addc_u32 s17, s41, s34
	s_lshl_b64 s[16:17], s[16:17], 12
	s_or_b32 s16, s16, s80
	s_add_u32 s16, s26, s16
	s_addc_u32 s17, s27, s17
	v_sub_u32_e32 v8, 0x7f, v197
	v_lshlrev_b32_e32 v9, 1, v203
	v_lshl_or_b32 v8, v8, 12, v9
	global_load_dwordx4 v[236:239], v8, s[16:17]
	v_add_u32_e32 v9, 0xfffe0000, v8
	global_load_dwordx4 v[240:243], v9, s[16:17]
	v_add_u32_e32 v12, 0xfffe0000, v9
	global_load_dwordx4 v[244:247], v12, s[16:17]

.Lre_m2:
	s_or_b64 exec, exec, s[16:17]
	v_cvt_pk_bf16_f32 v8, v112, v113
	v_cvt_pk_bf16_f32 v9, v114, v115
	ds_write_b64 v3, v[8:9]
	v_cvt_pk_bf16_f32 v12, v116, v117
	v_cvt_pk_bf16_f32 v13, v118, v119
	ds_write_b64 v3, v[12:13] offset:16
	v_cvt_pk_bf16_f32 v8, v120, v121
	v_cvt_pk_bf16_f32 v9, v122, v123
	ds_write_b64 v3, v[8:9] offset:32
	v_cvt_pk_bf16_f32 v12, v124, v125
	v_cvt_pk_bf16_f32 v13, v126, v127
	ds_write_b64 v3, v[12:13] offset:48
	s_and_b64 vcc, exec, s[46:47]
	s_cbranch_vccz .Lre_noof
	s_add_u32 s16, s40, s28
	s_addc_u32 s17, s41, s34
	s_lshl_b64 s[16:17], s[16:17], 12
	s_or_b32 s16, s16, s80
	s_add_u32 s16, s26, s16
	s_addc_u32 s17, s27, s17
	v_sub_u32_e32 v2, 0x7f, v197
	v_lshlrev_b32_e32 v3, 1, v203
	v_lshl_or_b32 v2, v2, 12, v3
	v_add_u32_e32 v2, 0xfffa0000, v2
	global_load_dwordx4 v[136:139], v2, s[16:17]

.LBB0_974:
.Lret_nopf:
	v_readfirstlane_b32 s16, v207
	s_cmp_eq_u32 s16, 0
	s_cbranch_scc0 .Lret_f_dg1
	ds_read_b64_tr_b16 v[2:3], v235
	ds_read_b64_tr_b16 v[4:5], v255
	ds_read_b128 v[6:9], v195
	ds_read_b128 v[10:13], v195 offset:8704
	ds_read_b64_tr_b16 v[124:125], v235 offset:4096
	ds_read_b64_tr_b16 v[126:127], v255 offset:4096
	ds_read_b128 v[128:131], v195 offset:32
	ds_read_b128 v[132:135], v195 offset:8736
	ds_read_b64_tr_b16 v[112:113], v235 offset:8192
	ds_read_b64_tr_b16 v[114:115], v255 offset:8192
	s_waitcnt lgkmcnt(6)
	v_mfma_f32_32x32x16_bf16 v[96:111], v[2:5], v[6:9], v[96:111]
	ds_read_b128 v[120:123], v195 offset:8768
	v_mfma_f32_32x32x16_bf16 v[80:95], v[2:5], v[10:13], v[80:95]
	ds_read_b64_tr_b16 v[2:3], v235 offset:12288
	ds_read_b64_tr_b16 v[4:5], v255 offset:12288
	s_waitcnt lgkmcnt(5)
	v_mfma_f32_32x32x16_bf16 v[96:111], v[124:127], v[128:131], v[96:111]
	ds_read_b128 v[10:13], v195 offset:8800
	v_mfma_f32_32x32x16_bf16 v[80:95], v[124:127], v[132:135], v[80:95]
	s_waitcnt lgkmcnt(3)
	v_mfma_f32_32x32x16_bf16 v[80:95], v[112:115], v[120:123], v[80:95]
	s_waitcnt lgkmcnt(0)
	v_mfma_f32_32x32x16_bf16 v[80:95], v[2:5], v[10:13], v[80:95]
	s_branch .Lret_f_end
.Lret_f_dg1:
	ds_read_b64_tr_b16 v[2:3], v235
	ds_read_b64_tr_b16 v[4:5], v255
	ds_read_b128 v[6:9], v195
	ds_read_b128 v[10:13], v195 offset:8704
	ds_read_b64_tr_b16 v[124:125], v235 offset:4096
	ds_read_b64_tr_b16 v[126:127], v255 offset:4096
	ds_read_b128 v[128:131], v195 offset:32
	ds_read_b128 v[132:135], v195 offset:8736
	ds_read_b64_tr_b16 v[112:113], v235 offset:8192
	ds_read_b64_tr_b16 v[114:115], v255 offset:8192
	s_waitcnt lgkmcnt(6)
	v_mfma_f32_32x32x16_bf16 v[96:111], v[2:5], v[6:9], v[96:111]
	ds_read_b128 v[116:119], v195 offset:64
	ds_read_b128 v[120:123], v195 offset:8768
	v_mfma_f32_32x32x16_bf16 v[80:95], v[2:5], v[10:13], v[80:95]
	ds_read_b64_tr_b16 v[2:3], v235 offset:12288
	ds_read_b64_tr_b16 v[4:5], v255 offset:12288
	s_waitcnt lgkmcnt(6)
	v_mfma_f32_32x32x16_bf16 v[96:111], v[124:127], v[128:131], v[96:111]
	ds_read_b128 v[6:9], v195 offset:96
	ds_read_b128 v[10:13], v195 offset:8800
	v_mfma_f32_32x32x16_bf16 v[80:95], v[124:127], v[132:135], v[80:95]
	ds_read_b64_tr_b16 v[124:125], v235 offset:16384
	ds_read_b64_tr_b16 v[126:127], v255 offset:16384
	s_waitcnt lgkmcnt(6)
	v_mfma_f32_32x32x16_bf16 v[96:111], v[112:115], v[116:119], v[96:111]
	ds_read_b128 v[128:131], v195 offset:128
	ds_read_b128 v[132:135], v195 offset:8832
	v_mfma_f32_32x32x16_bf16 v[80:95], v[112:115], v[120:123], v[80:95]
	ds_read_b64_tr_b16 v[112:113], v235 offset:20480
	ds_read_b64_tr_b16 v[114:115], v255 offset:20480
	s_waitcnt lgkmcnt(6)
	v_mfma_f32_32x32x16_bf16 v[96:111], v[2:5], v[6:9], v[96:111]
	ds_read_b128 v[116:119], v195 offset:160
	ds_read_b128 v[120:123], v195 offset:8864
	v_mfma_f32_32x32x16_bf16 v[80:95], v[2:5], v[10:13], v[80:95]
	ds_read_b64_tr_b16 v[2:3], v235 offset:24576
	ds_read_b64_tr_b16 v[4:5], v255 offset:24576
	s_waitcnt lgkmcnt(6)
	v_mfma_f32_32x32x16_bf16 v[96:111], v[124:127], v[128:131], v[96:111]
	ds_read_b128 v[10:13], v195 offset:8896
	v_mfma_f32_32x32x16_bf16 v[80:95], v[124:127], v[132:135], v[80:95]
	ds_read_b64_tr_b16 v[124:125], v235 offset:28672
	ds_read_b64_tr_b16 v[126:127], v255 offset:28672
	s_waitcnt lgkmcnt(5)
	v_mfma_f32_32x32x16_bf16 v[96:111], v[112:115], v[116:119], v[96:111]
	ds_read_b128 v[132:135], v195 offset:8928
	v_mfma_f32_32x32x16_bf16 v[80:95], v[112:115], v[120:123], v[80:95]
	s_waitcnt lgkmcnt(3)
	v_mfma_f32_32x32x16_bf16 v[80:95], v[2:5], v[10:13], v[80:95]
	s_waitcnt lgkmcnt(0)
	v_mfma_f32_32x32x16_bf16 v[80:95], v[124:127], v[132:135], v[80:95]
.Lret_f_end:
	s_nop 3
	v_add_u32_e32 v1, v234, v207
	v_add_u32_e32 v10, 1, v1
	v_cvt_f32_i32_e32 v14, v10
	v_mul_f32_e32 v2, v232, v14
	v_exp_f32_e32 v4, v2
	v_lshlrev_b32_e32 v2, 3, v233
	v_mul_lo_u32 v3, v1, s68
	v_add3_u32 v5, v208, v2, v3
	v_mul_f32_e32 v2, v4, v96
	v_mul_f32_e32 v3, v4, v97
	v_cvt_pk_bf16_f32 v2, v2, v3
	v_mul_f32_e32 v3, v4, v98
	v_mul_f32_e32 v6, v4, v99
	v_cvt_pk_bf16_f32 v3, v3, v6
	v_add_u32_e32 v1, 33, v1
	ds_write_b64 v5, v[2:3] offset:34816
	v_mul_f32_e32 v2, v4, v100
	v_mul_f32_e32 v3, v4, v101
	v_cvt_f32_i32_e32 v1, v1
	v_cvt_pk_bf16_f32 v2, v2, v3
	v_mul_f32_e32 v3, v4, v102
	v_mul_f32_e32 v6, v4, v103
	v_cvt_pk_bf16_f32 v3, v3, v6
	ds_write_b64 v5, v[2:3] offset:34832
	v_mul_f32_e32 v2, v4, v104
	v_mul_f32_e32 v3, v4, v105
	v_cvt_pk_bf16_f32 v2, v2, v3
	v_mul_f32_e32 v3, v4, v106
	v_mul_f32_e32 v1, v232, v1
	v_mul_f32_e32 v6, v4, v107
	v_cvt_pk_bf16_f32 v3, v3, v6
	v_exp_f32_e32 v1, v1
	ds_write_b64 v5, v[2:3] offset:34848
	v_mul_f32_e32 v2, v4, v108
	v_mul_f32_e32 v3, v4, v109
	v_cvt_pk_bf16_f32 v2, v2, v3
	v_mul_f32_e32 v3, v4, v110
	v_mul_f32_e32 v4, v4, v111
	v_cvt_pk_bf16_f32 v3, v3, v4
	ds_write_b64 v5, v[2:3] offset:34864
	v_mul_f32_e32 v2, v1, v80
	v_mul_f32_e32 v3, v1, v81
	v_cvt_pk_bf16_f32 v2, v2, v3
	v_mul_f32_e32 v3, v1, v82
	v_mul_f32_e32 v4, v1, v83
	v_cvt_pk_bf16_f32 v3, v3, v4
	ds_write_b64 v5, v[2:3] offset:43520
	v_mul_f32_e32 v2, v1, v84
	v_mul_f32_e32 v3, v1, v85
	v_cvt_pk_bf16_f32 v2, v2, v3
	v_mul_f32_e32 v3, v1, v86
	v_mul_f32_e32 v4, v1, v87
	v_cvt_pk_bf16_f32 v3, v3, v4
	ds_write_b64 v5, v[2:3] offset:43536
	v_mul_f32_e32 v2, v1, v88
	v_mul_f32_e32 v3, v1, v89
	v_cvt_pk_bf16_f32 v2, v2, v3
	v_mul_f32_e32 v3, v1, v90
	s_add_u32 s16, s40, s28
	v_mul_f32_e32 v4, v1, v91
	v_cvt_pk_bf16_f32 v3, v3, v4
	s_addc_u32 s17, s41, s34
	ds_write_b64 v5, v[2:3] offset:43552
	v_mul_f32_e32 v2, v1, v92
	v_mul_f32_e32 v3, v1, v93
	s_lshl_b64 s[18:19], s[16:17], 12
	v_cvt_pk_bf16_f32 v2, v2, v3
	v_mul_f32_e32 v3, v1, v94
	s_or_b32 s18, s18, s80
	v_mul_f32_e32 v1, v1, v95
	v_cvt_pk_bf16_f32 v3, v3, v1
	s_add_u32 s56, s26, s18
	ds_write_b64 v5, v[2:3] offset:43568
	s_waitcnt lgkmcnt(0)
	s_barrier
	s_addc_u32 s57, s27, s19
	v_sub_u32_e32 v10, 0x7f, v197
	ds_read_b128 v[2:5], v228 offset:34816
	ds_read_b128 v[112:115], v228 offset:43520
	ds_read_b128 v[116:119], v228 offset:52224
	ds_read_b128 v[120:123], v228 offset:60928
	s_add_u32 s54, s64, s18
	v_cndmask_b32_e64 v1, v10, v197, s[44:45]
	s_addc_u32 s55, s65, s19
	s_lshl_b64 s[16:17], s[16:17], 5
	v_lshl_or_b32 v8, v1, 11, v203
	s_add_u32 s18, s78, s16
	v_ashrrev_i32_e32 v9, 31, v8
	s_addc_u32 s19, s79, s17
	v_lshl_add_u64 v[6:7], v[8:9], 1, s[56:57]
	s_mov_b64 s[16:17], -1
	s_and_b64 vcc, exec, s[46:47]
	v_mbcnt_hi_u32_b32 v1, -1, v226
	s_cbranch_vccz .LBB0_982
	v_lshl_add_u64 v[8:9], v[8:9], 1, s[54:55]
	s_waitcnt lgkmcnt(3)
	v_lshlrev_b32_e32 v80, 16, v2
	v_and_b32_e32 v81, 0xffff0000, v2
	v_lshlrev_b32_e32 v82, 16, v3
	v_and_b32_e32 v83, 0xffff0000, v3
	v_lshlrev_b32_e32 v84, 16, v4
	v_and_b32_e32 v85, 0xffff0000, v4
	v_lshlrev_b32_e32 v86, 16, v5
	v_and_b32_e32 v87, 0xffff0000, v5
	s_waitcnt vmcnt(3)
	v_lshlrev_b32_e32 v88, 16, v236
	v_and_b32_e32 v89, 0xffff0000, v236
	v_lshlrev_b32_e32 v90, 16, v237
	v_and_b32_e32 v91, 0xffff0000, v237
	v_lshlrev_b32_e32 v92, 16, v238
	v_and_b32_e32 v93, 0xffff0000, v238
	v_lshlrev_b32_e32 v94, 16, v239
	v_and_b32_e32 v95, 0xffff0000, v239
	v_add_f32_e32 v80, v88, v80
	v_add_f32_e32 v81, v89, v81
	v_add_f32_e32 v82, v90, v82
	v_add_f32_e32 v83, v91, v83
	v_add_f32_e32 v84, v92, v84
	v_add_f32_e32 v85, v93, v85
	v_add_f32_e32 v86, v94, v86
	v_add_f32_e32 v87, v95, v87
	v_lshlrev_b32_e32 v94, 3, v10
	v_ashrrev_i32_e32 v95, 31, v94
	v_lshl_add_u64 v[94:95], v[94:95], 2, s[18:19]
	v_add_f32_e32 v88, v80, v81
	v_add_f32_e32 v89, v82, v83
	v_add_f32_e32 v90, v84, v85
	v_add_f32_e32 v91, v86, v87
	v_mul_f32_e32 v12, v80, v80
	v_mul_f32_e32 v13, v82, v82
	v_mul_f32_e32 v14, v84, v84
	v_mul_f32_e32 v15, v86, v86
	v_add_f32_e32 v88, v88, v89
	v_add_f32_e32 v90, v90, v91
	v_fmac_f32_e32 v12, v81, v81
	v_fmac_f32_e32 v13, v83, v83
	v_fmac_f32_e32 v14, v85, v85
	v_fmac_f32_e32 v15, v87, v87
	v_add_f32_e32 v92, v88, v90
	v_add_f32_e32 v12, v12, v13
	v_add_f32_e32 v14, v14, v15
	v_add_f32_e32 v93, v12, v14
	v_cvt_pk_bf16_f32 v80, v80, v81
	v_cvt_pk_bf16_f32 v81, v82, v83
	v_cvt_pk_bf16_f32 v82, v84, v85
	v_cvt_pk_bf16_f32 v83, v86, v87
	v_add_f32_dpp v92, v92, v92 quad_perm:[1,0,3,2] row_mask:0xf bank_mask:0xf
	v_add_f32_dpp v93, v93, v93 quad_perm:[1,0,3,2] row_mask:0xf bank_mask:0xf
	s_nop 0
	v_add_f32_dpp v92, v92, v92 quad_perm:[2,3,0,1] row_mask:0xf bank_mask:0xf
	v_add_f32_dpp v93, v93, v93 quad_perm:[2,3,0,1] row_mask:0xf bank_mask:0xf
	s_nop 0
	v_add_f32_dpp v92, v92, v92 row_ror:4 row_mask:0xf bank_mask:0xf
	v_add_f32_dpp v93, v93, v93 row_ror:4 row_mask:0xf bank_mask:0xf
	s_nop 0
	v_add_f32_dpp v92, v92, v92 row_ror:8 row_mask:0xf bank_mask:0xf
	v_add_f32_dpp v93, v93, v93 row_ror:8 row_mask:0xf bank_mask:0xf
	s_nop 0
	global_store_dwordx4 v[8:9], v[80:83], off
	s_and_saveexec_b64 s[16:17], s[8:9]
	s_cbranch_execz .LBB0_981
	global_atomic_add_f32 v[94:95], v92, off
	global_atomic_add_f32 v[94:95], v93, off offset:4

.LBB0_984:
	v_sub_u32_e32 v10, 0x5f, v197
	s_waitcnt lgkmcnt(3)
	v_cndmask_b32_e64 v2, v10, v231, s[44:45]
	v_lshl_or_b32 v8, v2, 11, v203
	v_ashrrev_i32_e32 v9, 31, v8
	v_cndmask_b32_e64 v11, 0, 1, s[46:47]
	v_lshl_add_u64 v[6:7], v[8:9], 1, s[56:57]
	v_cmp_ne_u32_e64 s[16:17], 1, v11
	s_andn2_b64 vcc, exec, s[46:47]
	s_mov_b64 s[58:59], -1
	s_cbranch_vccnz .LBB0_988
	v_lshl_add_u64 v[8:9], v[8:9], 1, s[54:55]
	s_waitcnt lgkmcnt(2)
	v_lshlrev_b32_e32 v80, 16, v112
	v_and_b32_e32 v81, 0xffff0000, v112
	v_lshlrev_b32_e32 v82, 16, v113
	v_and_b32_e32 v83, 0xffff0000, v113
	v_lshlrev_b32_e32 v84, 16, v114
	v_and_b32_e32 v85, 0xffff0000, v114
	v_lshlrev_b32_e32 v86, 16, v115
	v_and_b32_e32 v87, 0xffff0000, v115
	s_waitcnt vmcnt(3)
	v_lshlrev_b32_e32 v88, 16, v240
	v_and_b32_e32 v89, 0xffff0000, v240
	v_lshlrev_b32_e32 v90, 16, v241
	v_and_b32_e32 v91, 0xffff0000, v241
	v_lshlrev_b32_e32 v92, 16, v242
	v_and_b32_e32 v93, 0xffff0000, v242
	v_lshlrev_b32_e32 v94, 16, v243
	v_and_b32_e32 v95, 0xffff0000, v243
	v_add_f32_e32 v80, v88, v80
	v_add_f32_e32 v81, v89, v81
	v_add_f32_e32 v82, v90, v82
	v_add_f32_e32 v83, v91, v83
	v_add_f32_e32 v84, v92, v84
	v_add_f32_e32 v85, v93, v85
	v_add_f32_e32 v86, v94, v86
	v_add_f32_e32 v87, v95, v87
	v_lshlrev_b32_e32 v94, 3, v10
	v_ashrrev_i32_e32 v95, 31, v94
	v_lshl_add_u64 v[94:95], v[94:95], 2, s[18:19]
	v_add_f32_e32 v88, v80, v81
	v_add_f32_e32 v89, v82, v83
	v_add_f32_e32 v90, v84, v85
	v_add_f32_e32 v91, v86, v87
	v_mul_f32_e32 v12, v80, v80
	v_mul_f32_e32 v13, v82, v82
	v_mul_f32_e32 v14, v84, v84
	v_mul_f32_e32 v15, v86, v86
	v_add_f32_e32 v88, v88, v89
	v_add_f32_e32 v90, v90, v91
	v_fmac_f32_e32 v12, v81, v81
	v_fmac_f32_e32 v13, v83, v83
	v_fmac_f32_e32 v14, v85, v85
	v_fmac_f32_e32 v15, v87, v87
	v_add_f32_e32 v92, v88, v90
	v_add_f32_e32 v12, v12, v13
	v_add_f32_e32 v14, v14, v15
	v_add_f32_e32 v93, v12, v14
	v_cvt_pk_bf16_f32 v80, v80, v81
	v_cvt_pk_bf16_f32 v81, v82, v83
	v_cvt_pk_bf16_f32 v82, v84, v85
	v_cvt_pk_bf16_f32 v83, v86, v87
	v_add_f32_dpp v92, v92, v92 quad_perm:[1,0,3,2] row_mask:0xf bank_mask:0xf
	v_add_f32_dpp v93, v93, v93 quad_perm:[1,0,3,2] row_mask:0xf bank_mask:0xf
	s_nop 0
	v_add_f32_dpp v92, v92, v92 quad_perm:[2,3,0,1] row_mask:0xf bank_mask:0xf
	v_add_f32_dpp v93, v93, v93 quad_perm:[2,3,0,1] row_mask:0xf bank_mask:0xf
	s_nop 0
	v_add_f32_dpp v92, v92, v92 row_ror:4 row_mask:0xf bank_mask:0xf
	v_add_f32_dpp v93, v93, v93 row_ror:4 row_mask:0xf bank_mask:0xf
	s_nop 0
	v_add_f32_dpp v92, v92, v92 row_ror:8 row_mask:0xf bank_mask:0xf
	v_add_f32_dpp v93, v93, v93 row_ror:8 row_mask:0xf bank_mask:0xf
	s_nop 0
	global_store_dwordx4 v[8:9], v[80:83], off
	s_and_saveexec_b64 s[58:59], s[8:9]
	s_cbranch_execz .LBB0_987
	global_atomic_add_f32 v[94:95], v92, off
	global_atomic_add_f32 v[94:95], v93, off offset:4

.LBB0_988:
	s_andn2_b64 vcc, exec, s[58:59]
	s_cbranch_vccnz .LBB0_990
	s_waitcnt lgkmcnt(2)
	global_store_dwordx4 v[6:7], v[112:115], off
.LBB0_990:
	v_sub_u32_e32 v10, 63, v197
	s_waitcnt lgkmcnt(2)
	v_cndmask_b32_e64 v2, v10, v230, s[44:45]
	v_lshl_or_b32 v8, v2, 11, v203
	v_ashrrev_i32_e32 v9, 31, v8
	v_lshl_add_u64 v[6:7], v[8:9], 1, s[56:57]
	s_and_b64 vcc, exec, s[16:17]
	s_mov_b64 s[58:59], -1
	s_cbranch_vccnz .LBB0_994
	v_lshl_add_u64 v[8:9], v[8:9], 1, s[54:55]
	s_waitcnt lgkmcnt(1)
	v_lshlrev_b32_e32 v80, 16, v116
	v_and_b32_e32 v81, 0xffff0000, v116
	v_lshlrev_b32_e32 v82, 16, v117
	v_and_b32_e32 v83, 0xffff0000, v117
	v_lshlrev_b32_e32 v84, 16, v118
	v_and_b32_e32 v85, 0xffff0000, v118
	v_lshlrev_b32_e32 v86, 16, v119
	v_and_b32_e32 v87, 0xffff0000, v119
	s_waitcnt vmcnt(3)
	v_lshlrev_b32_e32 v88, 16, v244
	v_and_b32_e32 v89, 0xffff0000, v244
	v_lshlrev_b32_e32 v90, 16, v245
	v_and_b32_e32 v91, 0xffff0000, v245
	v_lshlrev_b32_e32 v92, 16, v246
	v_and_b32_e32 v93, 0xffff0000, v246
	v_lshlrev_b32_e32 v94, 16, v247
	v_and_b32_e32 v95, 0xffff0000, v247
	v_add_f32_e32 v80, v88, v80
	v_add_f32_e32 v81, v89, v81
	v_add_f32_e32 v82, v90, v82
	v_add_f32_e32 v83, v91, v83
	v_add_f32_e32 v84, v92, v84
	v_add_f32_e32 v85, v93, v85
	v_add_f32_e32 v86, v94, v86
	v_add_f32_e32 v87, v95, v87
	v_lshlrev_b32_e32 v94, 3, v10
	v_ashrrev_i32_e32 v95, 31, v94
	v_lshl_add_u64 v[94:95], v[94:95], 2, s[18:19]
	v_add_f32_e32 v88, v80, v81
	v_add_f32_e32 v89, v82, v83
	v_add_f32_e32 v90, v84, v85
	v_add_f32_e32 v91, v86, v87
	v_mul_f32_e32 v12, v80, v80
	v_mul_f32_e32 v13, v82, v82
	v_mul_f32_e32 v14, v84, v84
	v_mul_f32_e32 v15, v86, v86
	v_add_f32_e32 v88, v88, v89
	v_add_f32_e32 v90, v90, v91
	v_fmac_f32_e32 v12, v81, v81
	v_fmac_f32_e32 v13, v83, v83
	v_fmac_f32_e32 v14, v85, v85
	v_fmac_f32_e32 v15, v87, v87
	v_add_f32_e32 v92, v88, v90
	v_add_f32_e32 v12, v12, v13
	v_add_f32_e32 v14, v14, v15
	v_add_f32_e32 v93, v12, v14
	v_cvt_pk_bf16_f32 v80, v80, v81
	v_cvt_pk_bf16_f32 v81, v82, v83
	v_cvt_pk_bf16_f32 v82, v84, v85
	v_cvt_pk_bf16_f32 v83, v86, v87
	v_add_f32_dpp v92, v92, v92 quad_perm:[1,0,3,2] row_mask:0xf bank_mask:0xf
	v_add_f32_dpp v93, v93, v93 quad_perm:[1,0,3,2] row_mask:0xf bank_mask:0xf
	s_nop 0
	v_add_f32_dpp v92, v92, v92 quad_perm:[2,3,0,1] row_mask:0xf bank_mask:0xf
	v_add_f32_dpp v93, v93, v93 quad_perm:[2,3,0,1] row_mask:0xf bank_mask:0xf
	s_nop 0
	v_add_f32_dpp v92, v92, v92 row_ror:4 row_mask:0xf bank_mask:0xf
	v_add_f32_dpp v93, v93, v93 row_ror:4 row_mask:0xf bank_mask:0xf
	s_nop 0
	v_add_f32_dpp v92, v92, v92 row_ror:8 row_mask:0xf bank_mask:0xf
	v_add_f32_dpp v93, v93, v93 row_ror:8 row_mask:0xf bank_mask:0xf
	s_nop 0
	global_store_dwordx4 v[8:9], v[80:83], off
	s_and_saveexec_b64 s[58:59], s[8:9]
	s_cbranch_execz .LBB0_993
	global_atomic_add_f32 v[94:95], v92, off
	global_atomic_add_f32 v[94:95], v93, off offset:4

.LBB0_994:
	s_andn2_b64 vcc, exec, s[58:59]
	s_cbranch_vccnz .LBB0_996
	s_waitcnt lgkmcnt(1)
	global_store_dwordx4 v[6:7], v[116:119], off
.LBB0_996:
	v_sub_u32_e32 v10, 31, v197
	s_waitcnt lgkmcnt(1)
	v_cndmask_b32_e64 v2, v10, v229, s[44:45]
	v_lshl_or_b32 v8, v2, 11, v203
	v_ashrrev_i32_e32 v9, 31, v8
	v_lshl_add_u64 v[6:7], v[8:9], 1, s[56:57]
	s_and_b64 vcc, exec, s[16:17]
	s_mov_b64 s[16:17], -1
	s_cbranch_vccnz .LBB0_1000
	v_lshl_add_u64 v[8:9], v[8:9], 1, s[54:55]
	s_waitcnt lgkmcnt(0)
	v_lshlrev_b32_e32 v80, 16, v120
	v_and_b32_e32 v81, 0xffff0000, v120
	v_lshlrev_b32_e32 v82, 16, v121
	v_and_b32_e32 v83, 0xffff0000, v121
	v_lshlrev_b32_e32 v84, 16, v122
	v_and_b32_e32 v85, 0xffff0000, v122
	v_lshlrev_b32_e32 v86, 16, v123
	v_and_b32_e32 v87, 0xffff0000, v123
	s_waitcnt vmcnt(3)
	v_lshlrev_b32_e32 v88, 16, v136
	v_and_b32_e32 v89, 0xffff0000, v136
	v_lshlrev_b32_e32 v90, 16, v137
	v_and_b32_e32 v91, 0xffff0000, v137
	v_lshlrev_b32_e32 v92, 16, v138
	v_and_b32_e32 v93, 0xffff0000, v138
	v_lshlrev_b32_e32 v94, 16, v139
	v_and_b32_e32 v95, 0xffff0000, v139
	v_add_f32_e32 v80, v88, v80
	v_add_f32_e32 v81, v89, v81
	v_add_f32_e32 v82, v90, v82
	v_add_f32_e32 v83, v91, v83
	v_add_f32_e32 v84, v92, v84
	v_add_f32_e32 v85, v93, v85
	v_add_f32_e32 v86, v94, v86
	v_add_f32_e32 v87, v95, v87
	v_lshlrev_b32_e32 v94, 3, v10
	v_ashrrev_i32_e32 v95, 31, v94
	v_lshl_add_u64 v[94:95], v[94:95], 2, s[18:19]
	v_add_f32_e32 v88, v80, v81
	v_add_f32_e32 v89, v82, v83
	v_add_f32_e32 v90, v84, v85
	v_add_f32_e32 v91, v86, v87
	v_mul_f32_e32 v12, v80, v80
	v_mul_f32_e32 v13, v82, v82
	v_mul_f32_e32 v14, v84, v84
	v_mul_f32_e32 v15, v86, v86
	v_add_f32_e32 v88, v88, v89
	v_add_f32_e32 v90, v90, v91
	v_fmac_f32_e32 v12, v81, v81
	v_fmac_f32_e32 v13, v83, v83
	v_fmac_f32_e32 v14, v85, v85
	v_fmac_f32_e32 v15, v87, v87
	v_add_f32_e32 v92, v88, v90
	v_add_f32_e32 v12, v12, v13
	v_add_f32_e32 v14, v14, v15
	v_add_f32_e32 v93, v12, v14
	v_cvt_pk_bf16_f32 v80, v80, v81
	v_cvt_pk_bf16_f32 v81, v82, v83
	v_cvt_pk_bf16_f32 v82, v84, v85
	v_cvt_pk_bf16_f32 v83, v86, v87
	v_add_f32_dpp v92, v92, v92 quad_perm:[1,0,3,2] row_mask:0xf bank_mask:0xf
	v_add_f32_dpp v93, v93, v93 quad_perm:[1,0,3,2] row_mask:0xf bank_mask:0xf
	s_nop 0
	v_add_f32_dpp v92, v92, v92 quad_perm:[2,3,0,1] row_mask:0xf bank_mask:0xf
	v_add_f32_dpp v93, v93, v93 quad_perm:[2,3,0,1] row_mask:0xf bank_mask:0xf
	s_nop 0
	v_add_f32_dpp v92, v92, v92 row_ror:4 row_mask:0xf bank_mask:0xf
	v_add_f32_dpp v93, v93, v93 row_ror:4 row_mask:0xf bank_mask:0xf
	s_nop 0
	v_add_f32_dpp v92, v92, v92 row_ror:8 row_mask:0xf bank_mask:0xf
	v_add_f32_dpp v93, v93, v93 row_ror:8 row_mask:0xf bank_mask:0xf
	s_nop 0
	global_store_dwordx4 v[8:9], v[80:83], off
	s_and_saveexec_b64 s[16:17], s[8:9]
	s_cbranch_execz .LBB0_999
	global_atomic_add_f32 v[94:95], v92, off
	global_atomic_add_f32 v[94:95], v93, off offset:4

.LBB0_1000:
	s_andn2_b64 vcc, exec, s[16:17]
	s_cbranch_vccnz .LBB0_1002
	s_waitcnt lgkmcnt(0)
	global_store_dwordx4 v[6:7], v[120:123], off
